# attention unit epilogue: 16 subln vector loads issued together instead of one load + vmcnt(0) per store
# baseline (speedup 1.0000x reference)
; #define LAS __attribute__((address_space(3)))
; __device__ __forceinline__ float xor32_get(float v, int xaddr) { return __builtin_bit_cast(float, __builtin_amdgcn_ds_bpermute(xaddr, __builtin_bit_cast(int, v))); }
; __device__ __forceinline__ void attn_phase(const LArgs& a, LAS unsigned char* lds) {
;     ...
;         const float ltot = lrun + xor32_get(lrun, xaddr); const float inv = 1.f / ltot;
;         LAS float* xch = (LAS float*)lds + pr * 4096;
;         if (mp == 1) { const float f = inv * lam;
; #pragma unroll
;             for (int d = 0; d < 4; ++d)
; #pragma unroll
;                 for (int r = 0; r < 16; ++r) xch[(d * 16 + r) * 64 + lane] = o[d][r] * f; }
;         __syncthreads();
;         if (mp == 0) {
;             float ss = 0.f;
; #pragma unroll
;             for (int d = 0; d < 4; ++d)
; #pragma unroll
;                 for (int r = 0; r < 16; ++r) { const float dv = o[d][r] * inv - xch[(d * 16 + r) * 64 + lane]; o[d][r] = dv; ss += dv * dv; }
.LBB0_343:
	s_or_b64 exec, exec, s[0:1]
	s_waitcnt lgkmcnt(0)
	s_barrier
	s_and_saveexec_b64 s[16:17], s[8:9]
	s_cbranch_execz .LBB0_318
	ds_read2st64_b32 v[72:73], v170 offset1:1
	ds_read2st64_b32 v[74:75], v170 offset0:2 offset1:3
	ds_read2st64_b32 v[76:77], v170 offset0:4 offset1:5
	ds_read2st64_b32 v[84:85], v170 offset0:6 offset1:7
	ds_read2st64_b32 v[92:93], v170 offset0:8 offset1:9
	ds_read2st64_b32 v[94:95], v170 offset0:10 offset1:11
	ds_read2st64_b32 v[112:113], v170 offset0:12 offset1:13
	ds_read2st64_b32 v[114:115], v170 offset0:14 offset1:15
	ds_read2st64_b32 v[116:117], v170 offset0:16 offset1:17
	ds_read2st64_b32 v[118:119], v170 offset0:18 offset1:19
	ds_read2st64_b32 v[120:121], v170 offset0:20 offset1:21
	ds_read2st64_b32 v[122:123], v170 offset0:22 offset1:23
	ds_read2st64_b32 v[124:125], v170 offset0:24 offset1:25
	ds_read2st64_b32 v[126:127], v170 offset0:26 offset1:27
	s_waitcnt vmcnt(3)
	ds_read2st64_b32 v[128:129], v170 offset0:28 offset1:29
	ds_read2st64_b32 v[130:131], v170 offset0:30 offset1:31
	s_waitcnt vmcnt(2)
	ds_read2st64_b32 v[132:133], v170 offset0:32 offset1:33
	ds_read2st64_b32 v[134:135], v170 offset0:34 offset1:35
	s_waitcnt vmcnt(1)
	ds_read2st64_b32 v[136:137], v170 offset0:36 offset1:37
	ds_read2st64_b32 v[138:139], v170 offset0:38 offset1:39
	s_waitcnt vmcnt(0)
	ds_read2st64_b32 v[140:141], v170 offset0:40 offset1:41
	ds_read2st64_b32 v[142:143], v170 offset0:42 offset1:43
	ds_read2st64_b32 v[158:159], v170 offset0:44 offset1:45
	ds_read2st64_b32 v[160:161], v170 offset0:46 offset1:47
	ds_read2st64_b32 v[64:65], v170 offset0:56 offset1:57
	ds_read2st64_b32 v[162:163], v170 offset0:48 offset1:49
	ds_read2st64_b32 v[182:183], v170 offset0:50 offset1:51
	ds_read2st64_b32 v[184:185], v170 offset0:52 offset1:53
	ds_read2st64_b32 v[186:187], v170 offset0:54 offset1:55
	ds_read2st64_b32 v[68:69], v170 offset0:58 offset1:59
	ds_read2st64_b32 v[78:79], v170 offset0:60 offset1:61
	ds_read2st64_b32 v[80:81], v170 offset0:62 offset1:63
	s_waitcnt lgkmcnt(7)
	v_fma_f32 v66, v8, v70, -v64
	v_fma_f32 v64, v9, v70, -v65
	s_waitcnt lgkmcnt(2)
	v_pk_fma_f32 v[68:69], v[10:11], v[70:71], v[68:69] op_sel_hi:[1,0,1] neg_lo:[0,0,1] neg_hi:[0,0,1]
	global_load_dwordx4 v[8:11], v[150:151], off
	global_load_dwordx4 v[96:99], v[150:151], off offset:32
	global_load_dwordx4 v[100:103], v[150:151], off offset:64
	global_load_dwordx4 v[104:107], v[150:151], off offset:96
	global_load_dwordx4 v[108:111], v[150:151], off offset:128
	global_load_dwordx4 v[174:177], v[150:151], off offset:160
	global_load_dwordx4 v[208:211], v[150:151], off offset:192
	global_load_dwordx4 v[212:215], v[150:151], off offset:224
	global_load_dwordx4 v[216:219], v[150:151], off offset:256
	global_load_dwordx4 v[224:227], v[150:151], off offset:288
	global_load_dwordx4 v[228:231], v[150:151], off offset:320
	global_load_dwordx4 v[232:235], v[150:151], off offset:352
	global_load_dwordx4 v[236:239], v[150:151], off offset:384
	global_load_dwordx4 v[240:243], v[150:151], off offset:416
	global_load_dwordx4 v[244:247], v[150:151], off offset:448
	global_load_dwordx4 v[248:251], v[150:151], off offset:480
	s_waitcnt lgkmcnt(1)
	v_pk_fma_f32 v[12:13], v[12:13], v[70:71], v[78:79] op_sel_hi:[1,0,1] neg_lo:[0,0,1] neg_hi:[0,0,1]
	s_waitcnt lgkmcnt(0)
	v_pk_fma_f32 v[14:15], v[14:15], v[70:71], v[80:81] op_sel_hi:[1,0,1] neg_lo:[0,0,1] neg_hi:[0,0,1]
	v_mov_b32_e32 v78, v48
	v_mov_b32_e32 v79, v50
	v_mov_b32_e32 v80, v72
	v_mov_b32_e32 v81, v74
	v_mov_b32_e32 v50, v49
	v_mov_b32_e32 v74, v73
	v_pk_fma_f32 v[78:79], v[78:79], v[70:71], v[80:81] op_sel_hi:[1,0,1] neg_lo:[0,0,1] neg_hi:[0,0,1]
	v_pk_fma_f32 v[82:83], v[50:51], v[70:71], v[74:75] op_sel_hi:[1,0,1] neg_lo:[0,0,1] neg_hi:[0,0,1]
	v_pk_mul_f32 v[188:189], v[78:79], v[78:79]
	v_pk_mul_f32 v[190:191], v[82:83], v[82:83]
	v_mov_b32_e32 v48, v52
	v_mov_b32_e32 v49, v54
	v_mov_b32_e32 v50, v76
	v_mov_b32_e32 v51, v84
	v_add_f32_e32 v65, v188, v190
	v_pk_fma_f32 v[80:81], v[48:49], v[70:71], v[50:51] op_sel_hi:[1,0,1] neg_lo:[0,0,1] neg_hi:[0,0,1]
	v_mov_b32_e32 v54, v53
	v_mov_b32_e32 v84, v77
	v_add_f32_e32 v65, v65, v189
	v_pk_mul_f32 v[202:203], v[80:81], v[80:81]
	v_pk_fma_f32 v[84:85], v[54:55], v[70:71], v[84:85] op_sel_hi:[1,0,1] neg_lo:[0,0,1] neg_hi:[0,0,1]
	v_add_f32_e32 v65, v65, v191
	v_pk_mul_f32 v[204:205], v[84:85], v[84:85]
	v_add_f32_e32 v65, v65, v202
	v_mov_b32_e32 v48, v56
	v_mov_b32_e32 v49, v58
	v_mov_b32_e32 v50, v92
	v_mov_b32_e32 v51, v94
	v_add_f32_e32 v65, v65, v204
	v_pk_fma_f32 v[74:75], v[48:49], v[70:71], v[50:51] op_sel_hi:[1,0,1] neg_lo:[0,0,1] neg_hi:[0,0,1]
	v_mov_b32_e32 v58, v57
	v_mov_b32_e32 v94, v93
	v_add_f32_e32 v65, v65, v203
	v_pk_mul_f32 v[206:207], v[74:75], v[74:75]
	v_pk_fma_f32 v[76:77], v[58:59], v[70:71], v[94:95] op_sel_hi:[1,0,1] neg_lo:[0,0,1] neg_hi:[0,0,1]
	v_add_f32_e32 v65, v65, v205
	v_pk_mul_f32 v[92:93], v[76:77], v[76:77]
	v_add_f32_e32 v65, v65, v206
	v_mov_b32_e32 v48, v60
	v_mov_b32_e32 v49, v62
	v_mov_b32_e32 v50, v112
	v_mov_b32_e32 v51, v114
	v_add_f32_e32 v65, v65, v92
	v_pk_fma_f32 v[72:73], v[48:49], v[70:71], v[50:51] op_sel_hi:[1,0,1] neg_lo:[0,0,1] neg_hi:[0,0,1]
	v_mov_b32_e32 v62, v61
	v_mov_b32_e32 v114, v113
	v_add_f32_e32 v65, v65, v207
	v_pk_mul_f32 v[94:95], v[72:73], v[72:73]
	v_pk_fma_f32 v[60:61], v[62:63], v[70:71], v[114:115] op_sel_hi:[1,0,1] neg_lo:[0,0,1] neg_hi:[0,0,1]
	v_add_f32_e32 v65, v65, v93
	v_pk_mul_f32 v[62:63], v[60:61], v[60:61]
	v_add_f32_e32 v65, v65, v94
	v_mov_b32_e32 v48, v32
	v_mov_b32_e32 v49, v34
	v_mov_b32_e32 v50, v116
	v_mov_b32_e32 v51, v118
	v_add_f32_e32 v62, v65, v62
; __device__ __forceinline__ float xor32_get(float v, int xaddr) { return __builtin_bit_cast(float, __builtin_amdgcn_ds_bpermute(xaddr, __builtin_bit_cast(int, v))); }
; __device__ __forceinline__ void attn_phase(const LArgs& a, LAS unsigned char* lds) {
;     ...
;         if (mp == 0) {
;             float ss = 0.f;
; #pragma unroll
;             for (int d = 0; d < 4; ++d)
; #pragma unroll
;                 for (int r = 0; r < 16; ++r) { const float dv = o[d][r] * inv - xch[(d * 16 + r) * 64 + lane]; o[d][r] = dv; ss += dv * dv; }
;             ss += xor32_get(ss, xaddr);
	v_pk_fma_f32 v[56:57], v[48:49], v[70:71], v[50:51] op_sel_hi:[1,0,1] neg_lo:[0,0,1] neg_hi:[0,0,1]
	v_mov_b32_e32 v34, v33
	v_mov_b32_e32 v118, v117
	v_add_f32_e32 v62, v62, v95
	v_pk_mul_f32 v[112:113], v[56:57], v[56:57]
	v_pk_fma_f32 v[58:59], v[34:35], v[70:71], v[118:119] op_sel_hi:[1,0,1] neg_lo:[0,0,1] neg_hi:[0,0,1]
	v_add_f32_e32 v62, v62, v63
	v_pk_mul_f32 v[114:115], v[58:59], v[58:59]
	v_add_f32_e32 v62, v62, v112
	v_mov_b32_e32 v32, v36
	v_mov_b32_e32 v33, v38
	v_mov_b32_e32 v34, v120
	v_mov_b32_e32 v35, v122
	v_add_f32_e32 v62, v62, v114
	v_pk_fma_f32 v[52:53], v[32:33], v[70:71], v[34:35] op_sel_hi:[1,0,1] neg_lo:[0,0,1] neg_hi:[0,0,1]
	v_mov_b32_e32 v38, v37
	v_mov_b32_e32 v122, v121
	v_add_f32_e32 v62, v62, v113
	v_pk_mul_f32 v[116:117], v[52:53], v[52:53]
	v_pk_fma_f32 v[54:55], v[38:39], v[70:71], v[122:123] op_sel_hi:[1,0,1] neg_lo:[0,0,1] neg_hi:[0,0,1]
	v_add_f32_e32 v62, v62, v115
	v_pk_mul_f32 v[118:119], v[54:55], v[54:55]
	v_add_f32_e32 v62, v62, v116
	v_mov_b32_e32 v32, v40
	v_mov_b32_e32 v33, v42
	v_mov_b32_e32 v34, v124
	v_mov_b32_e32 v35, v126
	v_add_f32_e32 v62, v62, v118
	v_pk_fma_f32 v[48:49], v[32:33], v[70:71], v[34:35] op_sel_hi:[1,0,1] neg_lo:[0,0,1] neg_hi:[0,0,1]
	v_mov_b32_e32 v42, v41
	v_mov_b32_e32 v126, v125
	v_add_f32_e32 v62, v62, v117
	v_pk_mul_f32 v[120:121], v[48:49], v[48:49]
	v_pk_fma_f32 v[50:51], v[42:43], v[70:71], v[126:127] op_sel_hi:[1,0,1] neg_lo:[0,0,1] neg_hi:[0,0,1]
	v_add_f32_e32 v62, v62, v119
	v_pk_mul_f32 v[122:123], v[50:51], v[50:51]
	v_add_f32_e32 v62, v62, v120
	v_mov_b32_e32 v32, v44
	v_mov_b32_e32 v33, v46
	v_mov_b32_e32 v34, v128
	v_mov_b32_e32 v35, v130
	v_add_f32_e32 v62, v62, v122
	v_pk_fma_f32 v[42:43], v[32:33], v[70:71], v[34:35] op_sel_hi:[1,0,1] neg_lo:[0,0,1] neg_hi:[0,0,1]
	v_mov_b32_e32 v46, v45
	v_mov_b32_e32 v130, v129
	v_add_f32_e32 v62, v62, v121
	v_pk_mul_f32 v[124:125], v[42:43], v[42:43]
	v_pk_fma_f32 v[44:45], v[46:47], v[70:71], v[130:131] op_sel_hi:[1,0,1] neg_lo:[0,0,1] neg_hi:[0,0,1]
	v_add_f32_e32 v62, v62, v123
	v_pk_mul_f32 v[46:47], v[44:45], v[44:45]
	v_add_f32_e32 v62, v62, v124
	v_mov_b32_e32 v32, v16
	v_mov_b32_e32 v33, v18
	v_mov_b32_e32 v34, v132
	v_mov_b32_e32 v35, v134
	v_add_f32_e32 v46, v62, v46
	v_pk_fma_f32 v[38:39], v[32:33], v[70:71], v[34:35] op_sel_hi:[1,0,1] neg_lo:[0,0,1] neg_hi:[0,0,1]
	v_mov_b32_e32 v18, v17
	v_mov_b32_e32 v134, v133
	v_add_f32_e32 v46, v46, v125
	v_pk_mul_f32 v[126:127], v[38:39], v[38:39]
	v_pk_fma_f32 v[40:41], v[18:19], v[70:71], v[134:135] op_sel_hi:[1,0,1] neg_lo:[0,0,1] neg_hi:[0,0,1]
	v_add_f32_e32 v46, v46, v47
	v_pk_mul_f32 v[128:129], v[40:41], v[40:41]
	v_add_f32_e32 v46, v46, v126
	v_mov_b32_e32 v16, v20
	v_mov_b32_e32 v17, v22
	v_mov_b32_e32 v18, v136
	v_mov_b32_e32 v19, v138
	v_add_f32_e32 v46, v46, v128
	v_pk_fma_f32 v[34:35], v[16:17], v[70:71], v[18:19] op_sel_hi:[1,0,1] neg_lo:[0,0,1] neg_hi:[0,0,1]
	v_mov_b32_e32 v22, v21
	v_mov_b32_e32 v138, v137
	v_add_f32_e32 v46, v46, v127
	v_pk_mul_f32 v[130:131], v[34:35], v[34:35]
	v_pk_fma_f32 v[36:37], v[22:23], v[70:71], v[138:139] op_sel_hi:[1,0,1] neg_lo:[0,0,1] neg_hi:[0,0,1]
	v_add_f32_e32 v46, v46, v129
	v_pk_mul_f32 v[132:133], v[36:37], v[36:37]
	v_add_f32_e32 v46, v46, v130
	v_mov_b32_e32 v16, v24
	v_mov_b32_e32 v17, v26
	v_mov_b32_e32 v18, v140
	v_mov_b32_e32 v19, v142
	v_add_f32_e32 v46, v46, v132
	v_pk_fma_f32 v[32:33], v[16:17], v[70:71], v[18:19] op_sel_hi:[1,0,1] neg_lo:[0,0,1] neg_hi:[0,0,1]
	v_mov_b32_e32 v26, v25
	v_mov_b32_e32 v142, v141
	v_add_f32_e32 v46, v46, v131
	v_pk_mul_f32 v[134:135], v[32:33], v[32:33]
	v_pk_fma_f32 v[24:25], v[26:27], v[70:71], v[142:143] op_sel_hi:[1,0,1] neg_lo:[0,0,1] neg_hi:[0,0,1]
	v_add_f32_e32 v46, v46, v133
	v_pk_mul_f32 v[26:27], v[24:25], v[24:25]
	v_add_f32_e32 v46, v46, v134
	v_mov_b32_e32 v16, v28
	v_mov_b32_e32 v17, v30
	v_mov_b32_e32 v18, v158
	v_mov_b32_e32 v19, v160
	v_add_f32_e32 v26, v46, v26
	v_pk_fma_f32 v[20:21], v[16:17], v[70:71], v[18:19] op_sel_hi:[1,0,1] neg_lo:[0,0,1] neg_hi:[0,0,1]
	v_mov_b32_e32 v30, v29
	v_mov_b32_e32 v160, v159
	v_add_f32_e32 v26, v26, v135
	v_pk_mul_f32 v[136:137], v[20:21], v[20:21]
	v_pk_fma_f32 v[22:23], v[30:31], v[70:71], v[160:161] op_sel_hi:[1,0,1] neg_lo:[0,0,1] neg_hi:[0,0,1]
	v_add_f32_e32 v26, v26, v27
	v_pk_mul_f32 v[28:29], v[22:23], v[22:23]
	v_add_f32_e32 v26, v26, v136
	v_mov_b32_e32 v16, v0
	v_mov_b32_e32 v17, v2
	v_mov_b32_e32 v18, v162
	v_mov_b32_e32 v19, v182
	v_add_f32_e32 v26, v26, v28
	v_pk_fma_f32 v[16:17], v[16:17], v[70:71], v[18:19] op_sel_hi:[1,0,1] neg_lo:[0,0,1] neg_hi:[0,0,1]
	v_mov_b32_e32 v2, v1
	v_mov_b32_e32 v182, v163
	v_add_f32_e32 v26, v26, v137
	v_pk_mul_f32 v[30:31], v[16:17], v[16:17]
	v_pk_fma_f32 v[18:19], v[2:3], v[70:71], v[182:183] op_sel_hi:[1,0,1] neg_lo:[0,0,1] neg_hi:[0,0,1]
	v_add_f32_e32 v26, v26, v29
	v_pk_mul_f32 v[0:1], v[18:19], v[18:19]
	v_add_f32_e32 v26, v26, v30
	v_mov_b32_e32 v2, v4
	v_mov_b32_e32 v3, v6
	v_mov_b32_e32 v138, v184
	v_mov_b32_e32 v139, v186
	v_add_f32_e32 v0, v26, v0
	v_pk_fma_f32 v[2:3], v[2:3], v[70:71], v[138:139] op_sel_hi:[1,0,1] neg_lo:[0,0,1] neg_hi:[0,0,1]
	v_mov_b32_e32 v6, v5
	v_mov_b32_e32 v186, v185
	v_add_f32_e32 v0, v0, v31
	v_pk_mul_f32 v[138:139], v[2:3], v[2:3]
	v_pk_fma_f32 v[4:5], v[6:7], v[70:71], v[186:187] op_sel_hi:[1,0,1] neg_lo:[0,0,1] neg_hi:[0,0,1]
	v_add_f32_e32 v0, v0, v1
	v_pk_mul_f32 v[6:7], v[4:5], v[4:5]
	v_add_f32_e32 v0, v0, v138
	v_add_f32_e32 v0, v0, v6
	v_add_f32_e32 v0, v0, v139
	v_add_f32_e32 v0, v0, v7
	v_fmac_f32_e32 v0, v66, v66
	v_pk_mul_f32 v[86:87], v[68:69], v[68:69]
	v_fmac_f32_e32 v0, v64, v64
	v_add_f32_e32 v0, v0, v86
	v_pk_mul_f32 v[88:89], v[12:13], v[12:13]
	v_add_f32_e32 v0, v0, v87
	v_add_f32_e32 v0, v0, v88
	v_pk_mul_f32 v[90:91], v[14:15], v[14:15]
	v_add_f32_e32 v0, v0, v89
	v_add_f32_e32 v0, v0, v90
	v_add_f32_e32 v6, v0, v91
	ds_bpermute_b32 v7, v165, v6
	s_waitcnt vmcnt(0)
; __device__ __forceinline__ float xor32_get(float v, int xaddr) { return __builtin_bit_cast(float, __builtin_amdgcn_ds_bpermute(xaddr, __builtin_bit_cast(int, v))); }
; __device__ __forceinline__ unsigned pk2(float lo, float hi) { return f2bf(lo) | (f2bf(hi) << 16); }
; __device__ __forceinline__ void attn_phase(const LArgs& a, LAS unsigned char* lds) {
;     ...
;             ss += xor32_get(ss, xaddr);
;             const float rn = (1.f / sqrtf(ss * (1.f / 128.f) + 1e-5f)) * 0.8f;
;             bf16* orow = act + (size_t)(b * SEQ + qb * 128 + pr * 32 + r32) * DM + h * 128;
; #pragma unroll
;             for (int d = 0; d < 4; ++d)
; #pragma unroll
;                 for (int j4 = 0; j4 < 4; ++j4) { const int dv0 = 32 * d + 8 * j4 + 4 * hi; const f32x4 g = *(const f32x4*)(subln + dv0);
;                     u32x2 w; w.x = pk2(o[d][4 * j4 + 0] * rn * g.x, o[d][4 * j4 + 1] * rn * g.y); w.y = pk2(o[d][4 * j4 + 2] * rn * g.z, o[d][4 * j4 + 3] * rn * g.w);
;                     *(u32x2*)(orow + dv0) = w; }
	v_mov_b32_e32 v26, v8
	v_mov_b32_e32 v27, v10
	v_lshlrev_b64 v[0:1], 12, v[156:157]
	v_lshl_add_u64 v[0:1], s[14:15], 0, v[0:1]
	s_waitcnt lgkmcnt(0)
	v_add_f32_e32 v6, v6, v7
	v_fmamk_f32 v6, v6, 0x3c000000, v197
	v_mul_f32_e32 v7, 0x4f800000, v6
	v_cmp_gt_f32_e32 vcc, s61, v6
	v_lshl_add_u64 v[0:1], v[0:1], 0, s[48:49]
	v_mov_b32_e32 v155, v173
	v_cndmask_b32_e32 v6, v6, v7, vcc
	v_sqrt_f32_e32 v7, v6
	v_lshl_add_u64 v[0:1], v[0:1], 0, v[154:155]
	v_mov_b32_e32 v65, v69
	v_mov_b32_e32 v67, v68
	v_add_u32_e32 v8, -1, v7
	v_fma_f32 v10, -v8, v7, v6
	v_cmp_ge_f32_e64 s[0:1], 0, v10
	v_add_u32_e32 v10, 1, v7
	s_nop 0
	v_cndmask_b32_e64 v8, v7, v8, s[0:1]
	v_fma_f32 v7, -v10, v7, v6
	v_cmp_lt_f32_e64 s[0:1], 0, v7
	s_nop 1
	v_cndmask_b32_e64 v7, v8, v10, s[0:1]
	v_mul_f32_e32 v8, 0x37800000, v7
	v_cndmask_b32_e32 v7, v7, v8, vcc
	v_cmp_class_f32_e32 vcc, v6, v194
	v_mov_b32_e32 v10, v9
	s_nop 0
	v_cndmask_b32_e32 v6, v7, v6, vcc
	v_div_scale_f32 v7, s[0:1], v6, v6, 1.0
	v_rcp_f32_e32 v8, v7
	s_nop 0
	v_fma_f32 v9, -v7, v8, 1.0
	v_fmac_f32_e32 v8, v9, v8
	v_div_scale_f32 v9, vcc, 1.0, v6, 1.0
	v_mul_f32_e32 v28, v9, v8
	v_fma_f32 v29, -v7, v28, v9
	v_fmac_f32_e32 v28, v29, v8
	v_fma_f32 v7, -v7, v28, v9
	v_div_fmas_f32 v7, v7, v8, v28
	v_div_fixup_f32 v6, v7, v6, 1.0
	v_mul_f32_e32 v6, 0x3f4ccccd, v6
	v_pk_mul_f32 v[8:9], v[78:79], v[6:7] op_sel_hi:[1,0]
	s_nop 0
	v_pk_mul_f32 v[8:9], v[26:27], v[8:9]
	v_pk_mul_f32 v[26:27], v[82:83], v[6:7] op_sel_hi:[1,0]
	v_and_b32_sdwa v7, v9, v198 dst_sel:DWORD dst_unused:UNUSED_PAD src0_sel:WORD_1 src1_sel:DWORD
	v_pk_mul_f32 v[10:11], v[10:11], v[26:27]
	v_and_b32_sdwa v26, v8, v198 dst_sel:DWORD dst_unused:UNUSED_PAD src0_sel:WORD_1 src1_sel:DWORD
	v_add3_u32 v8, v8, v26, s72
	v_add3_u32 v7, v9, v7, s72
	v_and_b32_sdwa v9, v11, v198 dst_sel:DWORD dst_unused:UNUSED_PAD src0_sel:WORD_1 src1_sel:DWORD
	v_and_b32_sdwa v26, v10, v198 dst_sel:DWORD dst_unused:UNUSED_PAD src0_sel:WORD_1 src1_sel:DWORD
	v_add3_u32 v9, v11, v9, s72
	v_add3_u32 v10, v10, v26, s72
	v_and_b32_e32 v9, 0xffff0000, v9
	v_and_b32_e32 v10, 0xffff0000, v10
	v_or_b32_sdwa v9, v9, v7 dst_sel:DWORD dst_unused:UNUSED_PAD src0_sel:DWORD src1_sel:WORD_1
	v_or_b32_sdwa v8, v10, v8 dst_sel:DWORD dst_unused:UNUSED_PAD src0_sel:DWORD src1_sel:WORD_1
	global_store_dwordx2 v[0:1], v[8:9], off
	v_pk_mul_f32 v[26:27], v[80:81], v[6:7] op_sel_hi:[1,0]
	v_mov_b32_e32 v8, v96
	v_mov_b32_e32 v9, v97
	v_mov_b32_e32 v10, v98
	v_mov_b32_e32 v11, v99
	v_mov_b32_e32 v28, v8
	v_mov_b32_e32 v29, v10
	v_pk_mul_f32 v[26:27], v[28:29], v[26:27]
	v_pk_mul_f32 v[28:29], v[84:85], v[6:7] op_sel_hi:[1,0]
	v_mov_b32_e32 v10, v9
	v_pk_mul_f32 v[8:9], v[10:11], v[28:29]
	v_and_b32_sdwa v10, v26, v198 dst_sel:DWORD dst_unused:UNUSED_PAD src0_sel:WORD_1 src1_sel:DWORD
	v_add3_u32 v10, v26, v10, s72
	v_and_b32_sdwa v11, v9, v198 dst_sel:DWORD dst_unused:UNUSED_PAD src0_sel:WORD_1 src1_sel:DWORD
	v_and_b32_sdwa v26, v8, v198 dst_sel:DWORD dst_unused:UNUSED_PAD src0_sel:WORD_1 src1_sel:DWORD
	v_and_b32_sdwa v7, v27, v198 dst_sel:DWORD dst_unused:UNUSED_PAD src0_sel:WORD_1 src1_sel:DWORD
	v_add3_u32 v9, v9, v11, s72
	v_add3_u32 v8, v8, v26, s72
	v_add3_u32 v7, v27, v7, s72
	v_and_b32_e32 v9, 0xffff0000, v9
	v_and_b32_e32 v8, 0xffff0000, v8
	v_or_b32_sdwa v9, v9, v7 dst_sel:DWORD dst_unused:UNUSED_PAD src0_sel:DWORD src1_sel:WORD_1
	v_or_b32_sdwa v8, v8, v10 dst_sel:DWORD dst_unused:UNUSED_PAD src0_sel:DWORD src1_sel:WORD_1
	global_store_dwordx2 v[0:1], v[8:9], off offset:16
	v_pk_mul_f32 v[26:27], v[74:75], v[6:7] op_sel_hi:[1,0]
	v_mov_b32_e32 v8, v100
	v_mov_b32_e32 v9, v101
	v_mov_b32_e32 v10, v102
	v_mov_b32_e32 v11, v103
	v_mov_b32_e32 v28, v8
	v_mov_b32_e32 v29, v10
	v_pk_mul_f32 v[26:27], v[28:29], v[26:27]
	v_pk_mul_f32 v[28:29], v[76:77], v[6:7] op_sel_hi:[1,0]
	v_mov_b32_e32 v10, v9
	v_pk_mul_f32 v[8:9], v[10:11], v[28:29]
	v_and_b32_sdwa v10, v26, v198 dst_sel:DWORD dst_unused:UNUSED_PAD src0_sel:WORD_1 src1_sel:DWORD
	v_add3_u32 v10, v26, v10, s72
	v_and_b32_sdwa v11, v9, v198 dst_sel:DWORD dst_unused:UNUSED_PAD src0_sel:WORD_1 src1_sel:DWORD
	v_and_b32_sdwa v26, v8, v198 dst_sel:DWORD dst_unused:UNUSED_PAD src0_sel:WORD_1 src1_sel:DWORD
	v_and_b32_sdwa v7, v27, v198 dst_sel:DWORD dst_unused:UNUSED_PAD src0_sel:WORD_1 src1_sel:DWORD
	v_add3_u32 v9, v9, v11, s72
	v_add3_u32 v8, v8, v26, s72
	v_add3_u32 v7, v27, v7, s72
	v_and_b32_e32 v9, 0xffff0000, v9
	v_and_b32_e32 v8, 0xffff0000, v8
	v_or_b32_sdwa v9, v9, v7 dst_sel:DWORD dst_unused:UNUSED_PAD src0_sel:DWORD src1_sel:WORD_1
	v_or_b32_sdwa v8, v8, v10 dst_sel:DWORD dst_unused:UNUSED_PAD src0_sel:DWORD src1_sel:WORD_1
	global_store_dwordx2 v[0:1], v[8:9], off offset:32
	v_pk_mul_f32 v[26:27], v[72:73], v[6:7] op_sel_hi:[1,0]
	v_pk_mul_f32 v[28:29], v[60:61], v[6:7] op_sel_hi:[1,0]
	v_mov_b32_e32 v8, v104
	v_mov_b32_e32 v9, v105
	v_mov_b32_e32 v10, v106
	v_mov_b32_e32 v11, v107
	v_mov_b32_e32 v30, v8
	v_mov_b32_e32 v31, v10
	v_mov_b32_e32 v10, v9
	v_pk_mul_f32 v[8:9], v[30:31], v[26:27]
	v_pk_mul_f32 v[10:11], v[10:11], v[28:29]
	v_and_b32_sdwa v7, v9, v198 dst_sel:DWORD dst_unused:UNUSED_PAD src0_sel:WORD_1 src1_sel:DWORD
	v_and_b32_sdwa v27, v11, v198 dst_sel:DWORD dst_unused:UNUSED_PAD src0_sel:WORD_1 src1_sel:DWORD
	v_and_b32_sdwa v28, v10, v198 dst_sel:DWORD dst_unused:UNUSED_PAD src0_sel:WORD_1 src1_sel:DWORD
	v_and_b32_sdwa v26, v8, v198 dst_sel:DWORD dst_unused:UNUSED_PAD src0_sel:WORD_1 src1_sel:DWORD
	v_add3_u32 v7, v9, v7, s72
	v_add3_u32 v9, v11, v27, s72
	v_add3_u32 v10, v10, v28, s72
	v_add3_u32 v8, v8, v26, s72
	v_and_b32_e32 v9, 0xffff0000, v9
	v_and_b32_e32 v10, 0xffff0000, v10
; __device__ __forceinline__ unsigned pk2(float lo, float hi) { return f2bf(lo) | (f2bf(hi) << 16); }
; __device__ __forceinline__ void attn_phase(const LArgs& a, LAS unsigned char* lds) {
;     ...
; #pragma unroll
;             for (int d = 0; d < 4; ++d)
; #pragma unroll
;                 for (int j4 = 0; j4 < 4; ++j4) { const int dv0 = 32 * d + 8 * j4 + 4 * hi; const f32x4 g = *(const f32x4*)(subln + dv0);
;                     u32x2 w; w.x = pk2(o[d][4 * j4 + 0] * rn * g.x, o[d][4 * j4 + 1] * rn * g.y); w.y = pk2(o[d][4 * j4 + 2] * rn * g.z, o[d][4 * j4 + 3] * rn * g.w);
;                     *(u32x2*)(orow + dv0) = w; }
	v_or_b32_sdwa v9, v9, v7 dst_sel:DWORD dst_unused:UNUSED_PAD src0_sel:DWORD src1_sel:WORD_1
	v_or_b32_sdwa v8, v10, v8 dst_sel:DWORD dst_unused:UNUSED_PAD src0_sel:DWORD src1_sel:WORD_1
	global_store_dwordx2 v[0:1], v[8:9], off offset:48
	v_pk_mul_f32 v[26:27], v[56:57], v[6:7] op_sel_hi:[1,0]
	v_pk_mul_f32 v[28:29], v[58:59], v[6:7] op_sel_hi:[1,0]
	v_mov_b32_e32 v8, v108
	v_mov_b32_e32 v9, v109
	v_mov_b32_e32 v10, v110
	v_mov_b32_e32 v11, v111
	v_mov_b32_e32 v30, v8
	v_mov_b32_e32 v31, v10
	v_mov_b32_e32 v10, v9
	v_pk_mul_f32 v[8:9], v[26:27], v[30:31]
	v_pk_mul_f32 v[10:11], v[28:29], v[10:11]
	v_and_b32_sdwa v7, v9, v198 dst_sel:DWORD dst_unused:UNUSED_PAD src0_sel:WORD_1 src1_sel:DWORD
	v_and_b32_sdwa v27, v11, v198 dst_sel:DWORD dst_unused:UNUSED_PAD src0_sel:WORD_1 src1_sel:DWORD
	v_and_b32_sdwa v28, v10, v198 dst_sel:DWORD dst_unused:UNUSED_PAD src0_sel:WORD_1 src1_sel:DWORD
	v_and_b32_sdwa v26, v8, v198 dst_sel:DWORD dst_unused:UNUSED_PAD src0_sel:WORD_1 src1_sel:DWORD
	v_add3_u32 v7, v9, v7, s72
	v_add3_u32 v9, v11, v27, s72
	v_add3_u32 v10, v10, v28, s72
	v_add3_u32 v8, v8, v26, s72
	v_and_b32_e32 v9, 0xffff0000, v9
	v_and_b32_e32 v10, 0xffff0000, v10
	v_or_b32_sdwa v9, v9, v7 dst_sel:DWORD dst_unused:UNUSED_PAD src0_sel:DWORD src1_sel:WORD_1
	v_or_b32_sdwa v8, v10, v8 dst_sel:DWORD dst_unused:UNUSED_PAD src0_sel:DWORD src1_sel:WORD_1
	global_store_dwordx2 v[0:1], v[8:9], off offset:64
	v_pk_mul_f32 v[26:27], v[52:53], v[6:7] op_sel_hi:[1,0]
	v_pk_mul_f32 v[28:29], v[54:55], v[6:7] op_sel_hi:[1,0]
	v_mov_b32_e32 v8, v174
	v_mov_b32_e32 v9, v175
	v_mov_b32_e32 v10, v176
	v_mov_b32_e32 v11, v177
	v_mov_b32_e32 v30, v8
	v_mov_b32_e32 v31, v10
	v_mov_b32_e32 v10, v9
	v_pk_mul_f32 v[8:9], v[26:27], v[30:31]
	v_pk_mul_f32 v[10:11], v[28:29], v[10:11]
	v_and_b32_sdwa v7, v9, v198 dst_sel:DWORD dst_unused:UNUSED_PAD src0_sel:WORD_1 src1_sel:DWORD
	v_and_b32_sdwa v27, v11, v198 dst_sel:DWORD dst_unused:UNUSED_PAD src0_sel:WORD_1 src1_sel:DWORD
	v_and_b32_sdwa v28, v10, v198 dst_sel:DWORD dst_unused:UNUSED_PAD src0_sel:WORD_1 src1_sel:DWORD
	v_and_b32_sdwa v26, v8, v198 dst_sel:DWORD dst_unused:UNUSED_PAD src0_sel:WORD_1 src1_sel:DWORD
	v_add3_u32 v7, v9, v7, s72
	v_add3_u32 v9, v11, v27, s72
	v_add3_u32 v10, v10, v28, s72
	v_add3_u32 v8, v8, v26, s72
	v_and_b32_e32 v9, 0xffff0000, v9
	v_and_b32_e32 v10, 0xffff0000, v10
	v_or_b32_sdwa v9, v9, v7 dst_sel:DWORD dst_unused:UNUSED_PAD src0_sel:DWORD src1_sel:WORD_1
	v_or_b32_sdwa v8, v10, v8 dst_sel:DWORD dst_unused:UNUSED_PAD src0_sel:DWORD src1_sel:WORD_1
	global_store_dwordx2 v[0:1], v[8:9], off offset:80
	v_pk_mul_f32 v[26:27], v[48:49], v[6:7] op_sel_hi:[1,0]
	v_pk_mul_f32 v[28:29], v[50:51], v[6:7] op_sel_hi:[1,0]
	v_mov_b32_e32 v8, v208
	v_mov_b32_e32 v9, v209
	v_mov_b32_e32 v10, v210
	v_mov_b32_e32 v11, v211
	v_mov_b32_e32 v30, v8
	v_mov_b32_e32 v31, v10
	v_mov_b32_e32 v10, v9
	v_pk_mul_f32 v[8:9], v[26:27], v[30:31]
	v_pk_mul_f32 v[10:11], v[28:29], v[10:11]
	v_and_b32_sdwa v7, v9, v198 dst_sel:DWORD dst_unused:UNUSED_PAD src0_sel:WORD_1 src1_sel:DWORD
	v_and_b32_sdwa v27, v11, v198 dst_sel:DWORD dst_unused:UNUSED_PAD src0_sel:WORD_1 src1_sel:DWORD
	v_and_b32_sdwa v28, v10, v198 dst_sel:DWORD dst_unused:UNUSED_PAD src0_sel:WORD_1 src1_sel:DWORD
	v_and_b32_sdwa v26, v8, v198 dst_sel:DWORD dst_unused:UNUSED_PAD src0_sel:WORD_1 src1_sel:DWORD
	v_add3_u32 v7, v9, v7, s72
	v_add3_u32 v9, v11, v27, s72
	v_add3_u32 v10, v10, v28, s72
	v_add3_u32 v8, v8, v26, s72
	v_and_b32_e32 v9, 0xffff0000, v9
	v_and_b32_e32 v10, 0xffff0000, v10
	v_or_b32_sdwa v9, v9, v7 dst_sel:DWORD dst_unused:UNUSED_PAD src0_sel:DWORD src1_sel:WORD_1
	v_or_b32_sdwa v8, v10, v8 dst_sel:DWORD dst_unused:UNUSED_PAD src0_sel:DWORD src1_sel:WORD_1
	global_store_dwordx2 v[0:1], v[8:9], off offset:96
	v_pk_mul_f32 v[26:27], v[42:43], v[6:7] op_sel_hi:[1,0]
	v_pk_mul_f32 v[28:29], v[44:45], v[6:7] op_sel_hi:[1,0]
	v_mov_b32_e32 v8, v212
	v_mov_b32_e32 v9, v213
	v_mov_b32_e32 v10, v214
	v_mov_b32_e32 v11, v215
	v_mov_b32_e32 v30, v8
	v_mov_b32_e32 v31, v10
	v_mov_b32_e32 v10, v9
	v_pk_mul_f32 v[8:9], v[26:27], v[30:31]
	v_pk_mul_f32 v[10:11], v[28:29], v[10:11]
	v_and_b32_sdwa v7, v9, v198 dst_sel:DWORD dst_unused:UNUSED_PAD src0_sel:WORD_1 src1_sel:DWORD
	v_and_b32_sdwa v27, v11, v198 dst_sel:DWORD dst_unused:UNUSED_PAD src0_sel:WORD_1 src1_sel:DWORD
	v_and_b32_sdwa v28, v10, v198 dst_sel:DWORD dst_unused:UNUSED_PAD src0_sel:WORD_1 src1_sel:DWORD
	v_and_b32_sdwa v26, v8, v198 dst_sel:DWORD dst_unused:UNUSED_PAD src0_sel:WORD_1 src1_sel:DWORD
	v_add3_u32 v7, v9, v7, s72
	v_add3_u32 v9, v11, v27, s72
	v_add3_u32 v10, v10, v28, s72
	v_add3_u32 v8, v8, v26, s72
	v_and_b32_e32 v9, 0xffff0000, v9
	v_and_b32_e32 v10, 0xffff0000, v10
	v_or_b32_sdwa v9, v9, v7 dst_sel:DWORD dst_unused:UNUSED_PAD src0_sel:DWORD src1_sel:WORD_1
	v_or_b32_sdwa v8, v10, v8 dst_sel:DWORD dst_unused:UNUSED_PAD src0_sel:DWORD src1_sel:WORD_1
	global_store_dwordx2 v[0:1], v[8:9], off offset:112
	v_pk_mul_f32 v[26:27], v[38:39], v[6:7] op_sel_hi:[1,0]
	v_pk_mul_f32 v[28:29], v[40:41], v[6:7] op_sel_hi:[1,0]
	v_mov_b32_e32 v8, v216
	v_mov_b32_e32 v9, v217
	v_mov_b32_e32 v10, v218
	v_mov_b32_e32 v11, v219
	v_mov_b32_e32 v30, v8
	v_mov_b32_e32 v31, v10
	v_mov_b32_e32 v10, v9
	v_pk_mul_f32 v[8:9], v[26:27], v[30:31]
	v_pk_mul_f32 v[10:11], v[28:29], v[10:11]
	v_and_b32_sdwa v7, v9, v198 dst_sel:DWORD dst_unused:UNUSED_PAD src0_sel:WORD_1 src1_sel:DWORD
	v_and_b32_sdwa v27, v11, v198 dst_sel:DWORD dst_unused:UNUSED_PAD src0_sel:WORD_1 src1_sel:DWORD
	v_and_b32_sdwa v28, v10, v198 dst_sel:DWORD dst_unused:UNUSED_PAD src0_sel:WORD_1 src1_sel:DWORD
; __device__ __forceinline__ unsigned pk2(float lo, float hi) { return f2bf(lo) | (f2bf(hi) << 16); }
; __device__ __forceinline__ void attn_phase(const LArgs& a, LAS unsigned char* lds) {
;     ...
; #pragma unroll
;             for (int d = 0; d < 4; ++d)
; #pragma unroll
;                 for (int j4 = 0; j4 < 4; ++j4) { const int dv0 = 32 * d + 8 * j4 + 4 * hi; const f32x4 g = *(const f32x4*)(subln + dv0);
;                     u32x2 w; w.x = pk2(o[d][4 * j4 + 0] * rn * g.x, o[d][4 * j4 + 1] * rn * g.y); w.y = pk2(o[d][4 * j4 + 2] * rn * g.z, o[d][4 * j4 + 3] * rn * g.w);
;                     *(u32x2*)(orow + dv0) = w; }
	v_and_b32_sdwa v26, v8, v198 dst_sel:DWORD dst_unused:UNUSED_PAD src0_sel:WORD_1 src1_sel:DWORD
	v_add3_u32 v7, v9, v7, s72
	v_add3_u32 v9, v11, v27, s72
	v_add3_u32 v10, v10, v28, s72
	v_add3_u32 v8, v8, v26, s72
	v_and_b32_e32 v9, 0xffff0000, v9
	v_and_b32_e32 v10, 0xffff0000, v10
	v_or_b32_sdwa v9, v9, v7 dst_sel:DWORD dst_unused:UNUSED_PAD src0_sel:DWORD src1_sel:WORD_1
	v_or_b32_sdwa v8, v10, v8 dst_sel:DWORD dst_unused:UNUSED_PAD src0_sel:DWORD src1_sel:WORD_1
	global_store_dwordx2 v[0:1], v[8:9], off offset:128
	v_pk_mul_f32 v[26:27], v[34:35], v[6:7] op_sel_hi:[1,0]
	v_pk_mul_f32 v[28:29], v[36:37], v[6:7] op_sel_hi:[1,0]
	v_mov_b32_e32 v8, v224
	v_mov_b32_e32 v9, v225
	v_mov_b32_e32 v10, v226
	v_mov_b32_e32 v11, v227
	v_mov_b32_e32 v30, v8
	v_mov_b32_e32 v31, v10
	v_mov_b32_e32 v10, v9
	v_pk_mul_f32 v[8:9], v[26:27], v[30:31]
	v_pk_mul_f32 v[10:11], v[28:29], v[10:11]
	v_and_b32_sdwa v7, v9, v198 dst_sel:DWORD dst_unused:UNUSED_PAD src0_sel:WORD_1 src1_sel:DWORD
	v_and_b32_sdwa v27, v11, v198 dst_sel:DWORD dst_unused:UNUSED_PAD src0_sel:WORD_1 src1_sel:DWORD
	v_and_b32_sdwa v28, v10, v198 dst_sel:DWORD dst_unused:UNUSED_PAD src0_sel:WORD_1 src1_sel:DWORD
	v_and_b32_sdwa v26, v8, v198 dst_sel:DWORD dst_unused:UNUSED_PAD src0_sel:WORD_1 src1_sel:DWORD
	v_add3_u32 v7, v9, v7, s72
	v_add3_u32 v9, v11, v27, s72
	v_add3_u32 v10, v10, v28, s72
	v_add3_u32 v8, v8, v26, s72
	v_and_b32_e32 v9, 0xffff0000, v9
	v_and_b32_e32 v10, 0xffff0000, v10
	v_or_b32_sdwa v9, v9, v7 dst_sel:DWORD dst_unused:UNUSED_PAD src0_sel:DWORD src1_sel:WORD_1
	v_or_b32_sdwa v8, v10, v8 dst_sel:DWORD dst_unused:UNUSED_PAD src0_sel:DWORD src1_sel:WORD_1
	global_store_dwordx2 v[0:1], v[8:9], off offset:144
	v_pk_mul_f32 v[26:27], v[32:33], v[6:7] op_sel_hi:[1,0]
	v_pk_mul_f32 v[24:25], v[24:25], v[6:7] op_sel_hi:[1,0]
	v_mov_b32_e32 v8, v228
	v_mov_b32_e32 v9, v229
	v_mov_b32_e32 v10, v230
	v_mov_b32_e32 v11, v231
	v_mov_b32_e32 v28, v8
	v_mov_b32_e32 v29, v10
	v_mov_b32_e32 v10, v9
	v_pk_mul_f32 v[8:9], v[26:27], v[28:29]
	v_pk_mul_f32 v[10:11], v[24:25], v[10:11]
	v_and_b32_sdwa v7, v9, v198 dst_sel:DWORD dst_unused:UNUSED_PAD src0_sel:WORD_1 src1_sel:DWORD
	v_and_b32_sdwa v25, v11, v198 dst_sel:DWORD dst_unused:UNUSED_PAD src0_sel:WORD_1 src1_sel:DWORD
	v_and_b32_sdwa v26, v10, v198 dst_sel:DWORD dst_unused:UNUSED_PAD src0_sel:WORD_1 src1_sel:DWORD
	v_and_b32_sdwa v24, v8, v198 dst_sel:DWORD dst_unused:UNUSED_PAD src0_sel:WORD_1 src1_sel:DWORD
	v_add3_u32 v7, v9, v7, s72
	v_add3_u32 v9, v11, v25, s72
	v_add3_u32 v10, v10, v26, s72
	v_add3_u32 v8, v8, v24, s72
	v_and_b32_e32 v9, 0xffff0000, v9
	v_and_b32_e32 v10, 0xffff0000, v10
	v_or_b32_sdwa v9, v9, v7 dst_sel:DWORD dst_unused:UNUSED_PAD src0_sel:DWORD src1_sel:WORD_1
	v_or_b32_sdwa v8, v10, v8 dst_sel:DWORD dst_unused:UNUSED_PAD src0_sel:DWORD src1_sel:WORD_1
	global_store_dwordx2 v[0:1], v[8:9], off offset:160
	v_pk_mul_f32 v[20:21], v[20:21], v[6:7] op_sel_hi:[1,0]
	v_pk_mul_f32 v[22:23], v[22:23], v[6:7] op_sel_hi:[1,0]
	v_mov_b32_e32 v8, v232
	v_mov_b32_e32 v9, v233
	v_mov_b32_e32 v10, v234
	v_mov_b32_e32 v11, v235
	v_mov_b32_e32 v24, v8
	v_mov_b32_e32 v25, v10
	v_mov_b32_e32 v10, v9
	v_pk_mul_f32 v[8:9], v[20:21], v[24:25]
	v_pk_mul_f32 v[10:11], v[22:23], v[10:11]
	v_and_b32_sdwa v7, v9, v198 dst_sel:DWORD dst_unused:UNUSED_PAD src0_sel:WORD_1 src1_sel:DWORD
	v_and_b32_sdwa v21, v11, v198 dst_sel:DWORD dst_unused:UNUSED_PAD src0_sel:WORD_1 src1_sel:DWORD
	v_and_b32_sdwa v22, v10, v198 dst_sel:DWORD dst_unused:UNUSED_PAD src0_sel:WORD_1 src1_sel:DWORD
	v_and_b32_sdwa v20, v8, v198 dst_sel:DWORD dst_unused:UNUSED_PAD src0_sel:WORD_1 src1_sel:DWORD
	v_add3_u32 v7, v9, v7, s72
	v_add3_u32 v9, v11, v21, s72
	v_add3_u32 v10, v10, v22, s72
	v_add3_u32 v8, v8, v20, s72
	v_and_b32_e32 v9, 0xffff0000, v9
	v_and_b32_e32 v10, 0xffff0000, v10
	v_or_b32_sdwa v9, v9, v7 dst_sel:DWORD dst_unused:UNUSED_PAD src0_sel:DWORD src1_sel:WORD_1
	v_or_b32_sdwa v8, v10, v8 dst_sel:DWORD dst_unused:UNUSED_PAD src0_sel:DWORD src1_sel:WORD_1
	global_store_dwordx2 v[0:1], v[8:9], off offset:176
	v_pk_mul_f32 v[16:17], v[16:17], v[6:7] op_sel_hi:[1,0]
	v_pk_mul_f32 v[18:19], v[18:19], v[6:7] op_sel_hi:[1,0]
	v_mov_b32_e32 v8, v236
	v_mov_b32_e32 v9, v237
	v_mov_b32_e32 v10, v238
	v_mov_b32_e32 v11, v239
	v_mov_b32_e32 v20, v8
	v_mov_b32_e32 v21, v10
	v_mov_b32_e32 v10, v9
	v_pk_mul_f32 v[8:9], v[16:17], v[20:21]
; __device__ __forceinline__ unsigned pk2(float lo, float hi) { return f2bf(lo) | (f2bf(hi) << 16); }
; __device__ __forceinline__ void attn_phase(const LArgs& a, LAS unsigned char* lds) {
;     ...
; #pragma unroll
;             for (int d = 0; d < 4; ++d)
; #pragma unroll
;                 for (int j4 = 0; j4 < 4; ++j4) { const int dv0 = 32 * d + 8 * j4 + 4 * hi; const f32x4 g = *(const f32x4*)(subln + dv0);
;                     u32x2 w; w.x = pk2(o[d][4 * j4 + 0] * rn * g.x, o[d][4 * j4 + 1] * rn * g.y); w.y = pk2(o[d][4 * j4 + 2] * rn * g.z, o[d][4 * j4 + 3] * rn * g.w);
;                     *(u32x2*)(orow + dv0) = w; }
	v_pk_mul_f32 v[10:11], v[18:19], v[10:11]
	v_and_b32_sdwa v7, v9, v198 dst_sel:DWORD dst_unused:UNUSED_PAD src0_sel:WORD_1 src1_sel:DWORD
	v_and_b32_sdwa v17, v11, v198 dst_sel:DWORD dst_unused:UNUSED_PAD src0_sel:WORD_1 src1_sel:DWORD
	v_and_b32_sdwa v18, v10, v198 dst_sel:DWORD dst_unused:UNUSED_PAD src0_sel:WORD_1 src1_sel:DWORD
	v_and_b32_sdwa v16, v8, v198 dst_sel:DWORD dst_unused:UNUSED_PAD src0_sel:WORD_1 src1_sel:DWORD
	v_add3_u32 v7, v9, v7, s72
	v_add3_u32 v9, v11, v17, s72
	v_add3_u32 v10, v10, v18, s72
	v_add3_u32 v8, v8, v16, s72
	v_and_b32_e32 v9, 0xffff0000, v9
	v_and_b32_e32 v10, 0xffff0000, v10
	v_or_b32_sdwa v9, v9, v7 dst_sel:DWORD dst_unused:UNUSED_PAD src0_sel:DWORD src1_sel:WORD_1
	v_or_b32_sdwa v8, v10, v8 dst_sel:DWORD dst_unused:UNUSED_PAD src0_sel:DWORD src1_sel:WORD_1
	global_store_dwordx2 v[0:1], v[8:9], off offset:192
	v_pk_mul_f32 v[4:5], v[4:5], v[6:7] op_sel_hi:[1,0]
	v_pk_mul_f32 v[2:3], v[2:3], v[6:7] op_sel_hi:[1,0]
	v_mov_b32_e32 v8, v240
	v_mov_b32_e32 v9, v241
	v_mov_b32_e32 v10, v242
	v_mov_b32_e32 v11, v243
	v_mov_b32_e32 v17, v10
	v_mov_b32_e32 v10, v9
	v_mov_b32_e32 v16, v8
	v_pk_mul_f32 v[4:5], v[4:5], v[10:11]
	v_pk_mul_f32 v[2:3], v[2:3], v[16:17]
	v_and_b32_sdwa v9, v5, v198 dst_sel:DWORD dst_unused:UNUSED_PAD src0_sel:WORD_1 src1_sel:DWORD
	v_and_b32_sdwa v10, v4, v198 dst_sel:DWORD dst_unused:UNUSED_PAD src0_sel:WORD_1 src1_sel:DWORD
	v_and_b32_sdwa v7, v3, v198 dst_sel:DWORD dst_unused:UNUSED_PAD src0_sel:WORD_1 src1_sel:DWORD
	v_and_b32_sdwa v8, v2, v198 dst_sel:DWORD dst_unused:UNUSED_PAD src0_sel:WORD_1 src1_sel:DWORD
	v_add3_u32 v5, v5, v9, s72
	v_add3_u32 v4, v4, v10, s72
	v_add3_u32 v2, v2, v8, s72
	v_add3_u32 v3, v3, v7, s72
	v_and_b32_e32 v5, 0xffff0000, v5
	v_and_b32_e32 v4, 0xffff0000, v4
	v_or_b32_sdwa v3, v5, v3 dst_sel:DWORD dst_unused:UNUSED_PAD src0_sel:DWORD src1_sel:WORD_1
	v_or_b32_sdwa v2, v4, v2 dst_sel:DWORD dst_unused:UNUSED_PAD src0_sel:DWORD src1_sel:WORD_1
	global_store_dwordx2 v[0:1], v[2:3], off offset:208
	v_pk_mul_f32 v[10:11], v[64:65], v[6:7] op_sel_hi:[1,0]
	v_pk_mul_f32 v[8:9], v[66:67], v[6:7] op_sel_hi:[1,0]
	v_mov_b32_e32 v2, v244
	v_mov_b32_e32 v3, v245
	v_mov_b32_e32 v4, v246
	v_mov_b32_e32 v5, v247
	v_mov_b32_e32 v17, v4
	v_mov_b32_e32 v4, v3
	v_mov_b32_e32 v16, v2
	v_pk_mul_f32 v[4:5], v[10:11], v[4:5]
	v_pk_mul_f32 v[2:3], v[8:9], v[16:17]
	v_and_b32_sdwa v9, v5, v198 dst_sel:DWORD dst_unused:UNUSED_PAD src0_sel:WORD_1 src1_sel:DWORD
	v_and_b32_sdwa v10, v4, v198 dst_sel:DWORD dst_unused:UNUSED_PAD src0_sel:WORD_1 src1_sel:DWORD
	v_and_b32_sdwa v7, v3, v198 dst_sel:DWORD dst_unused:UNUSED_PAD src0_sel:WORD_1 src1_sel:DWORD
	v_and_b32_sdwa v8, v2, v198 dst_sel:DWORD dst_unused:UNUSED_PAD src0_sel:WORD_1 src1_sel:DWORD
	v_add3_u32 v5, v5, v9, s72
	v_add3_u32 v4, v4, v10, s72
	v_add3_u32 v2, v2, v8, s72
	v_add3_u32 v3, v3, v7, s72
	v_and_b32_e32 v5, 0xffff0000, v5
	v_and_b32_e32 v4, 0xffff0000, v4
	v_or_b32_sdwa v3, v5, v3 dst_sel:DWORD dst_unused:UNUSED_PAD src0_sel:DWORD src1_sel:WORD_1
	v_or_b32_sdwa v2, v4, v2 dst_sel:DWORD dst_unused:UNUSED_PAD src0_sel:DWORD src1_sel:WORD_1
	global_store_dwordx2 v[0:1], v[2:3], off offset:224
	v_mov_b32_e32 v8, v12
	v_mov_b32_e32 v9, v14
	v_mov_b32_e32 v14, v13
	v_pk_mul_f32 v[8:9], v[8:9], v[6:7] op_sel_hi:[1,0]
	v_pk_mul_f32 v[6:7], v[14:15], v[6:7] op_sel_hi:[1,0]
	v_mov_b32_e32 v2, v248
	v_mov_b32_e32 v3, v249
	v_mov_b32_e32 v4, v250
	v_mov_b32_e32 v5, v251
	v_mov_b32_e32 v11, v4
	v_mov_b32_e32 v4, v3
	v_mov_b32_e32 v10, v2
	v_pk_mul_f32 v[4:5], v[6:7], v[4:5]
	v_pk_mul_f32 v[2:3], v[8:9], v[10:11]
	v_and_b32_sdwa v8, v5, v198 dst_sel:DWORD dst_unused:UNUSED_PAD src0_sel:WORD_1 src1_sel:DWORD
	v_and_b32_sdwa v9, v4, v198 dst_sel:DWORD dst_unused:UNUSED_PAD src0_sel:WORD_1 src1_sel:DWORD
	v_and_b32_sdwa v6, v3, v198 dst_sel:DWORD dst_unused:UNUSED_PAD src0_sel:WORD_1 src1_sel:DWORD
	v_and_b32_sdwa v7, v2, v198 dst_sel:DWORD dst_unused:UNUSED_PAD src0_sel:WORD_1 src1_sel:DWORD
	v_add3_u32 v5, v5, v8, s72
	v_add3_u32 v4, v4, v9, s72
	v_add3_u32 v2, v2, v7, s72
	v_add3_u32 v3, v3, v6, s72
	v_and_b32_e32 v5, 0xffff0000, v5
	v_and_b32_e32 v4, 0xffff0000, v4
	v_or_b32_sdwa v3, v5, v3 dst_sel:DWORD dst_unused:UNUSED_PAD src0_sel:DWORD src1_sel:WORD_1
	v_or_b32_sdwa v2, v4, v2 dst_sel:DWORD dst_unused:UNUSED_PAD src0_sel:DWORD src1_sel:WORD_1
	global_store_dwordx2 v[0:1], v[2:3], off offset:240
	s_branch .LBB0_318
